# first memory phase: partial lgkmcnt(8) stall removed (one full LDS drain per memory phase)
# speedup vs baseline: 1.0037x; 1.0037x over previous
.LBB0_103:
	s_ashr_i32 s23, s22, 31
	s_lshl_b64 s[2:3], s[22:23], 19
	s_add_u32 s58, s90, s2
	s_addc_u32 s59, s77, s3
	s_and_b64 s[2:3], s[46:47], exec
	s_cselect_b32 s1, s59, s49
	s_cselect_b32 s23, s58, s48
	s_add_u32 s34, s34, 0x3e080
	s_addc_u32 s35, s35, 0
	s_add_u32 s51, s48, 0x100
	v_mov_b32_e32 v2, 0
	s_addc_u32 s52, s49, 0
	s_mov_b32 s53, -2
	s_add_u32 s2, s34, 0xfffc2080
	s_addc_u32 s3, s35, -1
	s_add_i32 s12, 0, 0x10000
	v_add_u32_e32 v110, s12, v179
	ds_read_b128 v[98:101], v110
	ds_read_b128 v[102:105], v110 offset:1024
	ds_read_b128 v[106:109], v110 offset:2048
	ds_read_b128 v[110:113], v110 offset:3072
	s_cmp_eq_u32 s53, 12
	s_cselect_b32 s49, s97, s3
	s_cselect_b32 s48, s96, s2
	s_cselect_b32 s3, s1, s52
	s_cselect_b32 s2, s23, s51
	v_lshl_add_u64 v[174:175], s[34:35], 0, v[170:171]
	s_add_i32 m0, s85, 0xc000
	ds_read_b128 v[114:117], v184
	ds_read_b128 v[118:121], v184 offset:1024
	ds_read_b128 v[122:125], v184 offset:2048
	ds_read_b128 v[126:129], v184 offset:3072
	ds_read_b128 v[186:189], v184 offset:4096
	ds_read_b128 v[190:193], v184 offset:5120
	ds_read_b128 v[194:197], v184 offset:6144
	ds_read_b128 v[198:201], v184 offset:7168
	global_load_lds_dwordx4 v[174:175], off
	v_lshl_add_u64 v[174:175], s[34:35], 0, v[172:173]
	s_add_i32 m0, s85, 0xe000
	s_nop 0
	global_load_lds_dwordx4 v[174:175], off
	s_add_i32 s54, 0, 0x14000
	v_add_u32_e32 v174, s54, v179
	s_add_i32 s12, s12, s78
	ds_read_b128 v[226:229], v174
	ds_read_b128 v[230:233], v174 offset:1024
	ds_read_b128 v[234:237], v174 offset:2048
	ds_read_b128 v[242:245], v174 offset:3072
	s_waitcnt lgkmcnt(0)
	s_barrier
	s_waitcnt lgkmcnt(0)
	v_mfma_f32_16x16x32_bf16 v[158:161], v[98:101], v[114:117], 0
	v_mfma_f32_16x16x32_bf16 v[154:157], v[106:109], v[114:117], 0
	v_mfma_f32_16x16x32_bf16 v[150:153], v[98:101], v[122:125], 0
	v_mfma_f32_16x16x32_bf16 v[146:149], v[106:109], v[122:125], 0
	v_mfma_f32_16x16x32_bf16 v[142:145], v[98:101], v[186:189], 0
	v_mfma_f32_16x16x32_bf16 v[138:141], v[106:109], v[186:189], 0
	v_mfma_f32_16x16x32_bf16 v[134:137], v[98:101], v[194:197], 0
	v_mfma_f32_16x16x32_bf16 v[130:133], v[106:109], v[194:197], 0
	v_mfma_f32_16x16x32_bf16 v[158:161], v[102:105], v[118:121], v[158:161]
	v_mfma_f32_16x16x32_bf16 v[154:157], v[110:113], v[118:121], v[154:157]
	v_mfma_f32_16x16x32_bf16 v[150:153], v[102:105], v[126:129], v[150:153]
	v_mfma_f32_16x16x32_bf16 v[146:149], v[110:113], v[126:129], v[146:149]
	v_mfma_f32_16x16x32_bf16 v[142:145], v[102:105], v[190:193], v[142:145]
	v_mfma_f32_16x16x32_bf16 v[138:141], v[110:113], v[190:193], v[138:141]
	v_mfma_f32_16x16x32_bf16 v[134:137], v[102:105], v[198:201], v[134:137]
	v_mfma_f32_16x16x32_bf16 v[130:133], v[110:113], v[198:201], v[130:133]
	v_mfma_f32_16x16x32_bf16 v[62:65], v[226:229], v[114:117], 0
	v_mfma_f32_16x16x32_bf16 v[58:61], v[234:237], v[114:117], 0
	v_mfma_f32_16x16x32_bf16 v[54:57], v[226:229], v[122:125], 0
	v_mfma_f32_16x16x32_bf16 v[50:53], v[234:237], v[122:125], 0
	v_mfma_f32_16x16x32_bf16 v[46:49], v[226:229], v[186:189], 0
	v_mfma_f32_16x16x32_bf16 v[42:45], v[234:237], v[186:189], 0
	v_mfma_f32_16x16x32_bf16 v[38:41], v[226:229], v[194:197], 0
	v_mfma_f32_16x16x32_bf16 v[34:37], v[234:237], v[194:197], 0
	v_mfma_f32_16x16x32_bf16 v[62:65], v[230:233], v[118:121], v[62:65]
	v_mfma_f32_16x16x32_bf16 v[58:61], v[242:245], v[118:121], v[58:61]
	v_mfma_f32_16x16x32_bf16 v[54:57], v[230:233], v[126:129], v[54:57]
	v_mfma_f32_16x16x32_bf16 v[50:53], v[242:245], v[126:129], v[50:53]
	s_mov_b32 m0, s85
	v_lshl_add_u64 v[248:249], s[48:49], 0, v[162:163]
	v_mfma_f32_16x16x32_bf16 v[46:49], v[230:233], v[190:193], v[46:49]
	v_mfma_f32_16x16x32_bf16 v[42:45], v[242:245], v[190:193], v[42:45]
	v_mfma_f32_16x16x32_bf16 v[38:41], v[230:233], v[198:201], v[38:41]
	v_mfma_f32_16x16x32_bf16 v[34:37], v[242:245], v[198:201], v[34:37]
	s_barrier
	ds_read_b128 v[114:117], v184 offset:16384
	ds_read_b128 v[118:121], v184 offset:17408
	ds_read_b128 v[122:125], v184 offset:18432
	ds_read_b128 v[126:129], v184 offset:19456
	ds_read_b128 v[186:189], v184 offset:20480
	ds_read_b128 v[190:193], v184 offset:21504
	ds_read_b128 v[194:197], v184 offset:22528
	ds_read_b128 v[198:201], v184 offset:23552
	global_load_lds_dwordx4 v[248:249], off
	v_lshl_add_u64 v[250:251], s[48:49], 0, v[164:165]
	s_mov_b32 m0, s82
	s_nop 0
	global_load_lds_dwordx4 v[250:251], off
	v_lshl_add_u64 v[174:175], s[2:3], 0, v[0:1]
	s_mov_b32 m0, s12
	v_lshl_add_u64 v[246:247], s[2:3], 0, v[166:167]
	global_load_lds_dwordx4 v[174:175], off
	s_add_i32 m0, s12, 0x2000
	s_nop 0
	global_load_lds_dwordx4 v[246:247], off
	s_add_u32 s12, s2, 0x40000
	s_addc_u32 s13, s3, 0
	s_add_i32 s54, s54, s78
	v_lshl_add_u64 v[174:175], s[12:13], 0, v[0:1]
	s_mov_b32 m0, s54
	s_nop 0
	global_load_lds_dwordx4 v[174:175], off
	v_lshl_add_u64 v[174:175], s[12:13], 0, v[166:167]
	s_add_i32 m0, s54, 0x2000
	s_nop 0
	global_load_lds_dwordx4 v[174:175], off
	s_waitcnt vmcnt(6)
	s_nop 0
	s_waitcnt lgkmcnt(0)
	s_barrier
	s_waitcnt lgkmcnt(0)
	v_mfma_f32_16x16x32_bf16 v[94:97], v[98:101], v[114:117], 0
	v_mfma_f32_16x16x32_bf16 v[90:93], v[106:109], v[114:117], 0
	v_mfma_f32_16x16x32_bf16 v[86:89], v[98:101], v[122:125], 0
	v_mfma_f32_16x16x32_bf16 v[82:85], v[106:109], v[122:125], 0
	v_mfma_f32_16x16x32_bf16 v[78:81], v[98:101], v[186:189], 0
	v_mfma_f32_16x16x32_bf16 v[74:77], v[106:109], v[186:189], 0
	v_mfma_f32_16x16x32_bf16 v[70:73], v[98:101], v[194:197], 0
	v_mfma_f32_16x16x32_bf16 v[66:69], v[106:109], v[194:197], 0
	v_mfma_f32_16x16x32_bf16 v[94:97], v[102:105], v[118:121], v[94:97]
	v_mfma_f32_16x16x32_bf16 v[90:93], v[110:113], v[118:121], v[90:93]
	v_mfma_f32_16x16x32_bf16 v[86:89], v[102:105], v[126:129], v[86:89]
	v_mfma_f32_16x16x32_bf16 v[82:85], v[110:113], v[126:129], v[82:85]
	v_mfma_f32_16x16x32_bf16 v[78:81], v[102:105], v[190:193], v[78:81]
	v_mfma_f32_16x16x32_bf16 v[74:77], v[110:113], v[190:193], v[74:77]
	v_mfma_f32_16x16x32_bf16 v[70:73], v[102:105], v[198:201], v[70:73]
	v_mfma_f32_16x16x32_bf16 v[66:69], v[110:113], v[198:201], v[66:69]
	v_mfma_f32_16x16x32_bf16 v[30:33], v[226:229], v[114:117], 0
	v_mfma_f32_16x16x32_bf16 v[26:29], v[234:237], v[114:117], 0
	v_mfma_f32_16x16x32_bf16 v[22:25], v[226:229], v[122:125], 0
	v_mfma_f32_16x16x32_bf16 v[18:21], v[234:237], v[122:125], 0
	v_mfma_f32_16x16x32_bf16 v[14:17], v[226:229], v[186:189], 0
	v_mfma_f32_16x16x32_bf16 v[10:13], v[234:237], v[186:189], 0
	v_mfma_f32_16x16x32_bf16 v[6:9], v[226:229], v[194:197], 0
	v_mfma_f32_16x16x32_bf16 v[2:5], v[234:237], v[194:197], 0
	v_mfma_f32_16x16x32_bf16 v[30:33], v[230:233], v[118:121], v[30:33]
	v_mfma_f32_16x16x32_bf16 v[26:29], v[242:245], v[118:121], v[26:29]
	v_mfma_f32_16x16x32_bf16 v[22:25], v[230:233], v[126:129], v[22:25]
	v_mfma_f32_16x16x32_bf16 v[18:21], v[242:245], v[126:129], v[18:21]
	s_add_i32 s54, 0, 0x18000
	v_add_u32_e32 v110, s54, v179
	v_mfma_f32_16x16x32_bf16 v[14:17], v[230:233], v[190:193], v[14:17]
	v_mfma_f32_16x16x32_bf16 v[10:13], v[242:245], v[190:193], v[10:13]
	v_mfma_f32_16x16x32_bf16 v[6:9], v[230:233], v[198:201], v[6:9]
	v_mfma_f32_16x16x32_bf16 v[2:5], v[242:245], v[198:201], v[2:5]
	s_barrier
	ds_read_b128 v[98:101], v110
	ds_read_b128 v[102:105], v110 offset:1024
	ds_read_b128 v[106:109], v110 offset:2048
	ds_read_b128 v[110:113], v110 offset:3072
	s_add_u32 s12, s48, 0x3e000
	s_addc_u32 s13, s49, 0
	s_mov_b32 m0, s89
	v_lshl_add_u64 v[226:227], s[12:13], 0, v[162:163]
	ds_read_b128 v[114:117], v184 offset:32768
	ds_read_b128 v[118:121], v184 offset:33792
	ds_read_b128 v[122:125], v184 offset:34816
	ds_read_b128 v[126:129], v184 offset:35840
	ds_read_b128 v[186:189], v184 offset:36864
	ds_read_b128 v[190:193], v184 offset:37888
	ds_read_b128 v[194:197], v184 offset:38912
	ds_read_b128 v[198:201], v184 offset:39936
	global_load_lds_dwordx4 v[226:227], off
	v_lshl_add_u64 v[226:227], s[12:13], 0, v[164:165]
	s_mov_b32 m0, s91
	s_nop 0
	global_load_lds_dwordx4 v[226:227], off
	s_add_i32 s12, 0, 0x1c000
	s_add_i32 s13, s54, s78
	v_add_u32_e32 v242, s12, v179
	ds_read_b128 v[226:229], v242
	ds_read_b128 v[230:233], v242 offset:1024
	ds_read_b128 v[234:237], v242 offset:2048
	ds_read_b128 v[242:245], v242 offset:3072
	s_waitcnt lgkmcnt(0)
	s_barrier
	s_waitcnt lgkmcnt(0)
	s_nop 0
	v_mfma_f32_16x16x32_bf16 v[158:161], v[98:101], v[114:117], v[158:161]
	v_mfma_f32_16x16x32_bf16 v[154:157], v[106:109], v[114:117], v[154:157]
	v_mfma_f32_16x16x32_bf16 v[150:153], v[98:101], v[122:125], v[150:153]
	v_mfma_f32_16x16x32_bf16 v[146:149], v[106:109], v[122:125], v[146:149]
	v_mfma_f32_16x16x32_bf16 v[142:145], v[98:101], v[186:189], v[142:145]
	v_mfma_f32_16x16x32_bf16 v[138:141], v[106:109], v[186:189], v[138:141]
	v_mfma_f32_16x16x32_bf16 v[134:137], v[98:101], v[194:197], v[134:137]
	v_mfma_f32_16x16x32_bf16 v[130:133], v[106:109], v[194:197], v[130:133]
	v_mfma_f32_16x16x32_bf16 v[158:161], v[102:105], v[118:121], v[158:161]
	v_mfma_f32_16x16x32_bf16 v[154:157], v[110:113], v[118:121], v[154:157]
	v_mfma_f32_16x16x32_bf16 v[150:153], v[102:105], v[126:129], v[150:153]
	v_mfma_f32_16x16x32_bf16 v[146:149], v[110:113], v[126:129], v[146:149]
	v_mfma_f32_16x16x32_bf16 v[142:145], v[102:105], v[190:193], v[142:145]
	v_mfma_f32_16x16x32_bf16 v[138:141], v[110:113], v[190:193], v[138:141]
	v_mfma_f32_16x16x32_bf16 v[134:137], v[102:105], v[198:201], v[134:137]
	v_mfma_f32_16x16x32_bf16 v[130:133], v[110:113], v[198:201], v[130:133]
	v_mfma_f32_16x16x32_bf16 v[62:65], v[226:229], v[114:117], v[62:65]
	v_mfma_f32_16x16x32_bf16 v[58:61], v[234:237], v[114:117], v[58:61]
	v_mfma_f32_16x16x32_bf16 v[54:57], v[226:229], v[122:125], v[54:57]
	v_mfma_f32_16x16x32_bf16 v[50:53], v[234:237], v[122:125], v[50:53]
	v_mfma_f32_16x16x32_bf16 v[46:49], v[226:229], v[186:189], v[46:49]
	v_mfma_f32_16x16x32_bf16 v[42:45], v[234:237], v[186:189], v[42:45]
	v_mfma_f32_16x16x32_bf16 v[38:41], v[226:229], v[194:197], v[38:41]
	v_mfma_f32_16x16x32_bf16 v[34:37], v[234:237], v[194:197], v[34:37]
	v_mfma_f32_16x16x32_bf16 v[62:65], v[230:233], v[118:121], v[62:65]
	v_mfma_f32_16x16x32_bf16 v[58:61], v[242:245], v[118:121], v[58:61]
	v_mfma_f32_16x16x32_bf16 v[54:57], v[230:233], v[126:129], v[54:57]
	v_mfma_f32_16x16x32_bf16 v[50:53], v[242:245], v[126:129], v[50:53]
	s_mov_b32 m0, s79
	v_lshl_add_u64 v[174:175], v[248:249], 0, s[20:21]
	v_mfma_f32_16x16x32_bf16 v[46:49], v[230:233], v[190:193], v[46:49]
	v_mfma_f32_16x16x32_bf16 v[42:45], v[242:245], v[190:193], v[42:45]
	v_mfma_f32_16x16x32_bf16 v[38:41], v[230:233], v[198:201], v[38:41]
	v_mfma_f32_16x16x32_bf16 v[34:37], v[242:245], v[198:201], v[34:37]
	s_barrier
	ds_read_b128 v[114:117], v184 offset:49152
	ds_read_b128 v[118:121], v184 offset:50176
	ds_read_b128 v[122:125], v184 offset:51200
	ds_read_b128 v[126:129], v184 offset:52224
	ds_read_b128 v[186:189], v184 offset:53248
	ds_read_b128 v[190:193], v184 offset:54272
	ds_read_b128 v[194:197], v184 offset:55296
	ds_read_b128 v[198:201], v184 offset:56320
	global_load_lds_dwordx4 v[174:175], off
	v_lshl_add_u64 v[174:175], v[250:251], 0, s[20:21]
	s_mov_b32 m0, s87
	s_nop 0
	global_load_lds_dwordx4 v[174:175], off
	v_lshl_add_u64 v[174:175], s[2:3], 0, v[0:1]
	v_lshl_add_u64 v[174:175], v[174:175], 0, s[20:21]
	s_mov_b32 m0, s13
	s_nop 0
	global_load_lds_dwordx4 v[174:175], off
	v_lshl_add_u64 v[174:175], v[246:247], 0, s[20:21]
	s_add_i32 m0, s13, 0x2000
	s_nop 0
	global_load_lds_dwordx4 v[174:175], off
	s_add_u32 s2, s2, 0x40080
	s_addc_u32 s3, s3, 0
	s_add_i32 s12, s12, s78
	v_lshl_add_u64 v[174:175], s[2:3], 0, v[0:1]
	s_mov_b32 m0, s12
	s_nop 0
	global_load_lds_dwordx4 v[174:175], off
	v_lshl_add_u64 v[174:175], s[2:3], 0, v[166:167]
	s_add_i32 m0, s12, 0x2000
	s_nop 0
	global_load_lds_dwordx4 v[174:175], off
	s_waitcnt vmcnt(6)
	s_nop 0
	s_waitcnt lgkmcnt(0)
	s_barrier
	s_waitcnt lgkmcnt(0)
	s_nop 0
	v_mfma_f32_16x16x32_bf16 v[94:97], v[98:101], v[114:117], v[94:97]
	v_mfma_f32_16x16x32_bf16 v[90:93], v[106:109], v[114:117], v[90:93]
	v_mfma_f32_16x16x32_bf16 v[86:89], v[98:101], v[122:125], v[86:89]
	v_mfma_f32_16x16x32_bf16 v[82:85], v[106:109], v[122:125], v[82:85]
	v_mfma_f32_16x16x32_bf16 v[78:81], v[98:101], v[186:189], v[78:81]
	v_mfma_f32_16x16x32_bf16 v[74:77], v[106:109], v[186:189], v[74:77]
	v_mfma_f32_16x16x32_bf16 v[70:73], v[98:101], v[194:197], v[70:73]
	v_mfma_f32_16x16x32_bf16 v[66:69], v[106:109], v[194:197], v[66:69]
	v_mfma_f32_16x16x32_bf16 v[94:97], v[102:105], v[118:121], v[94:97]
	v_mfma_f32_16x16x32_bf16 v[90:93], v[110:113], v[118:121], v[90:93]
	v_mfma_f32_16x16x32_bf16 v[86:89], v[102:105], v[126:129], v[86:89]
	v_mfma_f32_16x16x32_bf16 v[82:85], v[110:113], v[126:129], v[82:85]
	v_mfma_f32_16x16x32_bf16 v[78:81], v[102:105], v[190:193], v[78:81]
	v_mfma_f32_16x16x32_bf16 v[74:77], v[110:113], v[190:193], v[74:77]
	v_mfma_f32_16x16x32_bf16 v[70:73], v[102:105], v[198:201], v[70:73]
	v_mfma_f32_16x16x32_bf16 v[66:69], v[110:113], v[198:201], v[66:69]
	v_mfma_f32_16x16x32_bf16 v[30:33], v[226:229], v[114:117], v[30:33]
	v_mfma_f32_16x16x32_bf16 v[26:29], v[234:237], v[114:117], v[26:29]
	v_mfma_f32_16x16x32_bf16 v[22:25], v[226:229], v[122:125], v[22:25]
	v_mfma_f32_16x16x32_bf16 v[18:21], v[234:237], v[122:125], v[18:21]
	v_mfma_f32_16x16x32_bf16 v[14:17], v[226:229], v[186:189], v[14:17]
	v_mfma_f32_16x16x32_bf16 v[10:13], v[234:237], v[186:189], v[10:13]
	v_mfma_f32_16x16x32_bf16 v[6:9], v[226:229], v[194:197], v[6:9]
	v_mfma_f32_16x16x32_bf16 v[2:5], v[234:237], v[194:197], v[2:5]
	v_mfma_f32_16x16x32_bf16 v[30:33], v[230:233], v[118:121], v[30:33]
	v_mfma_f32_16x16x32_bf16 v[26:29], v[242:245], v[118:121], v[26:29]
	v_mfma_f32_16x16x32_bf16 v[22:25], v[230:233], v[126:129], v[22:25]
	v_mfma_f32_16x16x32_bf16 v[18:21], v[242:245], v[126:129], v[18:21]
	s_add_i32 s53, s53, 2
	s_add_u32 s34, s34, 0x100
	s_addc_u32 s35, s35, 0
	s_add_u32 s51, s51, 0x100
	s_addc_u32 s52, s52, 0
	s_cmp_gt_u32 s53, 13
	v_mfma_f32_16x16x32_bf16 v[14:17], v[230:233], v[190:193], v[14:17]
	v_mfma_f32_16x16x32_bf16 v[10:13], v[242:245], v[190:193], v[10:13]
	v_mfma_f32_16x16x32_bf16 v[6:9], v[230:233], v[198:201], v[6:9]
	v_mfma_f32_16x16x32_bf16 v[2:5], v[242:245], v[198:201], v[2:5]
	s_barrier
	s_cbranch_scc1 .Lpeel_x_0
.LBB0_104:
	s_add_u32 s2, s34, 0xfffc2080
	s_addc_u32 s3, s35, -1
	s_add_i32 s12, 0, 0x10000
	v_add_u32_e32 v110, s12, v179
	ds_read_b128 v[98:101], v110
	ds_read_b128 v[102:105], v110 offset:1024
	ds_read_b128 v[106:109], v110 offset:2048
	ds_read_b128 v[110:113], v110 offset:3072
	s_cmp_eq_u32 s53, 12
	s_cselect_b32 s49, s97, s3
	s_cselect_b32 s48, s96, s2
	s_cselect_b32 s3, s1, s52
	s_cselect_b32 s2, s23, s51
	v_lshl_add_u64 v[174:175], s[34:35], 0, v[170:171]
	s_add_i32 m0, s85, 0xc000
	ds_read_b128 v[114:117], v184
	ds_read_b128 v[118:121], v184 offset:1024
	ds_read_b128 v[122:125], v184 offset:2048
	ds_read_b128 v[126:129], v184 offset:3072
	ds_read_b128 v[186:189], v184 offset:4096
	ds_read_b128 v[190:193], v184 offset:5120
	ds_read_b128 v[194:197], v184 offset:6144
	ds_read_b128 v[198:201], v184 offset:7168
	global_load_lds_dwordx4 v[174:175], off
	v_lshl_add_u64 v[174:175], s[34:35], 0, v[172:173]
	s_add_i32 m0, s85, 0xe000
	s_nop 0
	global_load_lds_dwordx4 v[174:175], off
	s_add_i32 s54, 0, 0x14000
	v_add_u32_e32 v174, s54, v179
	s_add_i32 s12, s12, s78
	ds_read_b128 v[226:229], v174
	ds_read_b128 v[230:233], v174 offset:1024
	ds_read_b128 v[234:237], v174 offset:2048
	ds_read_b128 v[242:245], v174 offset:3072
	s_waitcnt lgkmcnt(0)
	s_barrier
	s_waitcnt lgkmcnt(0)
	s_nop 0
	v_mfma_f32_16x16x32_bf16 v[158:161], v[98:101], v[114:117], v[158:161]
	v_mfma_f32_16x16x32_bf16 v[154:157], v[106:109], v[114:117], v[154:157]
	v_mfma_f32_16x16x32_bf16 v[150:153], v[98:101], v[122:125], v[150:153]
	v_mfma_f32_16x16x32_bf16 v[146:149], v[106:109], v[122:125], v[146:149]
	v_mfma_f32_16x16x32_bf16 v[142:145], v[98:101], v[186:189], v[142:145]
	v_mfma_f32_16x16x32_bf16 v[138:141], v[106:109], v[186:189], v[138:141]
	v_mfma_f32_16x16x32_bf16 v[134:137], v[98:101], v[194:197], v[134:137]
	v_mfma_f32_16x16x32_bf16 v[130:133], v[106:109], v[194:197], v[130:133]
	v_mfma_f32_16x16x32_bf16 v[158:161], v[102:105], v[118:121], v[158:161]
	v_mfma_f32_16x16x32_bf16 v[154:157], v[110:113], v[118:121], v[154:157]
	v_mfma_f32_16x16x32_bf16 v[150:153], v[102:105], v[126:129], v[150:153]
	v_mfma_f32_16x16x32_bf16 v[146:149], v[110:113], v[126:129], v[146:149]
	v_mfma_f32_16x16x32_bf16 v[142:145], v[102:105], v[190:193], v[142:145]
	v_mfma_f32_16x16x32_bf16 v[138:141], v[110:113], v[190:193], v[138:141]
	v_mfma_f32_16x16x32_bf16 v[134:137], v[102:105], v[198:201], v[134:137]
	v_mfma_f32_16x16x32_bf16 v[130:133], v[110:113], v[198:201], v[130:133]
	v_mfma_f32_16x16x32_bf16 v[62:65], v[226:229], v[114:117], v[62:65]
	v_mfma_f32_16x16x32_bf16 v[58:61], v[234:237], v[114:117], v[58:61]
	v_mfma_f32_16x16x32_bf16 v[54:57], v[226:229], v[122:125], v[54:57]
	v_mfma_f32_16x16x32_bf16 v[50:53], v[234:237], v[122:125], v[50:53]
	v_mfma_f32_16x16x32_bf16 v[46:49], v[226:229], v[186:189], v[46:49]
	v_mfma_f32_16x16x32_bf16 v[42:45], v[234:237], v[186:189], v[42:45]
	v_mfma_f32_16x16x32_bf16 v[38:41], v[226:229], v[194:197], v[38:41]
	v_mfma_f32_16x16x32_bf16 v[34:37], v[234:237], v[194:197], v[34:37]
	v_mfma_f32_16x16x32_bf16 v[62:65], v[230:233], v[118:121], v[62:65]
	v_mfma_f32_16x16x32_bf16 v[58:61], v[242:245], v[118:121], v[58:61]
	v_mfma_f32_16x16x32_bf16 v[54:57], v[230:233], v[126:129], v[54:57]
	v_mfma_f32_16x16x32_bf16 v[50:53], v[242:245], v[126:129], v[50:53]
	s_mov_b32 m0, s85
	v_lshl_add_u64 v[248:249], s[48:49], 0, v[162:163]
	v_mfma_f32_16x16x32_bf16 v[46:49], v[230:233], v[190:193], v[46:49]
	v_mfma_f32_16x16x32_bf16 v[42:45], v[242:245], v[190:193], v[42:45]
	v_mfma_f32_16x16x32_bf16 v[38:41], v[230:233], v[198:201], v[38:41]
	v_mfma_f32_16x16x32_bf16 v[34:37], v[242:245], v[198:201], v[34:37]
	s_barrier
	ds_read_b128 v[114:117], v184 offset:16384
	ds_read_b128 v[118:121], v184 offset:17408
	ds_read_b128 v[122:125], v184 offset:18432
	ds_read_b128 v[126:129], v184 offset:19456
	ds_read_b128 v[186:189], v184 offset:20480
	ds_read_b128 v[190:193], v184 offset:21504
	ds_read_b128 v[194:197], v184 offset:22528
	ds_read_b128 v[198:201], v184 offset:23552
	global_load_lds_dwordx4 v[248:249], off
	v_lshl_add_u64 v[250:251], s[48:49], 0, v[164:165]
	s_mov_b32 m0, s82
	s_nop 0
	global_load_lds_dwordx4 v[250:251], off
	v_lshl_add_u64 v[174:175], s[2:3], 0, v[0:1]
	s_mov_b32 m0, s12
	v_lshl_add_u64 v[246:247], s[2:3], 0, v[166:167]
	global_load_lds_dwordx4 v[174:175], off
	s_add_i32 m0, s12, 0x2000
	s_nop 0
	global_load_lds_dwordx4 v[246:247], off
	s_add_u32 s12, s2, 0x40000
	s_addc_u32 s13, s3, 0
	s_add_i32 s54, s54, s78
	v_lshl_add_u64 v[174:175], s[12:13], 0, v[0:1]
	s_mov_b32 m0, s54
	s_nop 0
	global_load_lds_dwordx4 v[174:175], off
	v_lshl_add_u64 v[174:175], s[12:13], 0, v[166:167]
	s_add_i32 m0, s54, 0x2000
	s_nop 0
	global_load_lds_dwordx4 v[174:175], off
	s_waitcnt vmcnt(6)
	s_nop 0
	s_waitcnt lgkmcnt(0)
	s_barrier
	s_waitcnt lgkmcnt(0)
	v_mfma_f32_16x16x32_bf16 v[94:97], v[98:101], v[114:117], v[94:97]
	v_mfma_f32_16x16x32_bf16 v[90:93], v[106:109], v[114:117], v[90:93]
	v_mfma_f32_16x16x32_bf16 v[86:89], v[98:101], v[122:125], v[86:89]
	v_mfma_f32_16x16x32_bf16 v[82:85], v[106:109], v[122:125], v[82:85]
	v_mfma_f32_16x16x32_bf16 v[78:81], v[98:101], v[186:189], v[78:81]
	v_mfma_f32_16x16x32_bf16 v[74:77], v[106:109], v[186:189], v[74:77]
	v_mfma_f32_16x16x32_bf16 v[70:73], v[98:101], v[194:197], v[70:73]
	v_mfma_f32_16x16x32_bf16 v[66:69], v[106:109], v[194:197], v[66:69]
	v_mfma_f32_16x16x32_bf16 v[94:97], v[102:105], v[118:121], v[94:97]
	v_mfma_f32_16x16x32_bf16 v[90:93], v[110:113], v[118:121], v[90:93]
	v_mfma_f32_16x16x32_bf16 v[86:89], v[102:105], v[126:129], v[86:89]
	v_mfma_f32_16x16x32_bf16 v[82:85], v[110:113], v[126:129], v[82:85]
	v_mfma_f32_16x16x32_bf16 v[78:81], v[102:105], v[190:193], v[78:81]
	v_mfma_f32_16x16x32_bf16 v[74:77], v[110:113], v[190:193], v[74:77]
	v_mfma_f32_16x16x32_bf16 v[70:73], v[102:105], v[198:201], v[70:73]
	v_mfma_f32_16x16x32_bf16 v[66:69], v[110:113], v[198:201], v[66:69]
	v_mfma_f32_16x16x32_bf16 v[30:33], v[226:229], v[114:117], v[30:33]
	v_mfma_f32_16x16x32_bf16 v[26:29], v[234:237], v[114:117], v[26:29]
	v_mfma_f32_16x16x32_bf16 v[22:25], v[226:229], v[122:125], v[22:25]
	v_mfma_f32_16x16x32_bf16 v[18:21], v[234:237], v[122:125], v[18:21]
	v_mfma_f32_16x16x32_bf16 v[14:17], v[226:229], v[186:189], v[14:17]
	v_mfma_f32_16x16x32_bf16 v[10:13], v[234:237], v[186:189], v[10:13]
	v_mfma_f32_16x16x32_bf16 v[6:9], v[226:229], v[194:197], v[6:9]
	v_mfma_f32_16x16x32_bf16 v[2:5], v[234:237], v[194:197], v[2:5]
	v_mfma_f32_16x16x32_bf16 v[30:33], v[230:233], v[118:121], v[30:33]
	v_mfma_f32_16x16x32_bf16 v[26:29], v[242:245], v[118:121], v[26:29]
	v_mfma_f32_16x16x32_bf16 v[22:25], v[230:233], v[126:129], v[22:25]
	v_mfma_f32_16x16x32_bf16 v[18:21], v[242:245], v[126:129], v[18:21]
	s_add_i32 s54, 0, 0x18000
	v_add_u32_e32 v110, s54, v179
	v_mfma_f32_16x16x32_bf16 v[14:17], v[230:233], v[190:193], v[14:17]
	v_mfma_f32_16x16x32_bf16 v[10:13], v[242:245], v[190:193], v[10:13]
	v_mfma_f32_16x16x32_bf16 v[6:9], v[230:233], v[198:201], v[6:9]
	v_mfma_f32_16x16x32_bf16 v[2:5], v[242:245], v[198:201], v[2:5]
	s_barrier
	ds_read_b128 v[98:101], v110
	ds_read_b128 v[102:105], v110 offset:1024
	ds_read_b128 v[106:109], v110 offset:2048
	ds_read_b128 v[110:113], v110 offset:3072
	s_add_u32 s12, s48, 0x3e000
	s_addc_u32 s13, s49, 0
	s_mov_b32 m0, s89
	v_lshl_add_u64 v[226:227], s[12:13], 0, v[162:163]
	ds_read_b128 v[114:117], v184 offset:32768
	ds_read_b128 v[118:121], v184 offset:33792
	ds_read_b128 v[122:125], v184 offset:34816
	ds_read_b128 v[126:129], v184 offset:35840
	ds_read_b128 v[186:189], v184 offset:36864
	ds_read_b128 v[190:193], v184 offset:37888
	ds_read_b128 v[194:197], v184 offset:38912
	ds_read_b128 v[198:201], v184 offset:39936
	global_load_lds_dwordx4 v[226:227], off
	v_lshl_add_u64 v[226:227], s[12:13], 0, v[164:165]
	s_mov_b32 m0, s91
	s_nop 0
	global_load_lds_dwordx4 v[226:227], off
	s_add_i32 s12, 0, 0x1c000
	s_add_i32 s13, s54, s78
	v_add_u32_e32 v242, s12, v179
	ds_read_b128 v[226:229], v242
	ds_read_b128 v[230:233], v242 offset:1024
	ds_read_b128 v[234:237], v242 offset:2048
	ds_read_b128 v[242:245], v242 offset:3072
	s_waitcnt lgkmcnt(0)
	s_barrier
	s_waitcnt lgkmcnt(0)
	s_nop 0
	v_mfma_f32_16x16x32_bf16 v[158:161], v[98:101], v[114:117], v[158:161]
	v_mfma_f32_16x16x32_bf16 v[154:157], v[106:109], v[114:117], v[154:157]
	v_mfma_f32_16x16x32_bf16 v[150:153], v[98:101], v[122:125], v[150:153]
	v_mfma_f32_16x16x32_bf16 v[146:149], v[106:109], v[122:125], v[146:149]
	v_mfma_f32_16x16x32_bf16 v[142:145], v[98:101], v[186:189], v[142:145]
	v_mfma_f32_16x16x32_bf16 v[138:141], v[106:109], v[186:189], v[138:141]
	v_mfma_f32_16x16x32_bf16 v[134:137], v[98:101], v[194:197], v[134:137]
	v_mfma_f32_16x16x32_bf16 v[130:133], v[106:109], v[194:197], v[130:133]
	v_mfma_f32_16x16x32_bf16 v[158:161], v[102:105], v[118:121], v[158:161]
	v_mfma_f32_16x16x32_bf16 v[154:157], v[110:113], v[118:121], v[154:157]
	v_mfma_f32_16x16x32_bf16 v[150:153], v[102:105], v[126:129], v[150:153]
	v_mfma_f32_16x16x32_bf16 v[146:149], v[110:113], v[126:129], v[146:149]
	v_mfma_f32_16x16x32_bf16 v[142:145], v[102:105], v[190:193], v[142:145]
	v_mfma_f32_16x16x32_bf16 v[138:141], v[110:113], v[190:193], v[138:141]
	v_mfma_f32_16x16x32_bf16 v[134:137], v[102:105], v[198:201], v[134:137]
	v_mfma_f32_16x16x32_bf16 v[130:133], v[110:113], v[198:201], v[130:133]
	v_mfma_f32_16x16x32_bf16 v[62:65], v[226:229], v[114:117], v[62:65]
	v_mfma_f32_16x16x32_bf16 v[58:61], v[234:237], v[114:117], v[58:61]
	v_mfma_f32_16x16x32_bf16 v[54:57], v[226:229], v[122:125], v[54:57]
	v_mfma_f32_16x16x32_bf16 v[50:53], v[234:237], v[122:125], v[50:53]
	v_mfma_f32_16x16x32_bf16 v[46:49], v[226:229], v[186:189], v[46:49]
	v_mfma_f32_16x16x32_bf16 v[42:45], v[234:237], v[186:189], v[42:45]
	v_mfma_f32_16x16x32_bf16 v[38:41], v[226:229], v[194:197], v[38:41]
	v_mfma_f32_16x16x32_bf16 v[34:37], v[234:237], v[194:197], v[34:37]
	v_mfma_f32_16x16x32_bf16 v[62:65], v[230:233], v[118:121], v[62:65]
	v_mfma_f32_16x16x32_bf16 v[58:61], v[242:245], v[118:121], v[58:61]
	v_mfma_f32_16x16x32_bf16 v[54:57], v[230:233], v[126:129], v[54:57]
	v_mfma_f32_16x16x32_bf16 v[50:53], v[242:245], v[126:129], v[50:53]
	s_mov_b32 m0, s79
	v_lshl_add_u64 v[174:175], v[248:249], 0, s[20:21]
	v_mfma_f32_16x16x32_bf16 v[46:49], v[230:233], v[190:193], v[46:49]
	v_mfma_f32_16x16x32_bf16 v[42:45], v[242:245], v[190:193], v[42:45]
	v_mfma_f32_16x16x32_bf16 v[38:41], v[230:233], v[198:201], v[38:41]
	v_mfma_f32_16x16x32_bf16 v[34:37], v[242:245], v[198:201], v[34:37]
	s_barrier
	ds_read_b128 v[114:117], v184 offset:49152
	ds_read_b128 v[118:121], v184 offset:50176
	ds_read_b128 v[122:125], v184 offset:51200
	ds_read_b128 v[126:129], v184 offset:52224
	ds_read_b128 v[186:189], v184 offset:53248
	ds_read_b128 v[190:193], v184 offset:54272
	ds_read_b128 v[194:197], v184 offset:55296
	ds_read_b128 v[198:201], v184 offset:56320
	global_load_lds_dwordx4 v[174:175], off
	v_lshl_add_u64 v[174:175], v[250:251], 0, s[20:21]
	s_mov_b32 m0, s87
	s_nop 0
	global_load_lds_dwordx4 v[174:175], off
	v_lshl_add_u64 v[174:175], s[2:3], 0, v[0:1]
	v_lshl_add_u64 v[174:175], v[174:175], 0, s[20:21]
	s_mov_b32 m0, s13
	s_nop 0
	global_load_lds_dwordx4 v[174:175], off
	v_lshl_add_u64 v[174:175], v[246:247], 0, s[20:21]
	s_add_i32 m0, s13, 0x2000
	s_nop 0
	global_load_lds_dwordx4 v[174:175], off
	s_add_u32 s2, s2, 0x40080
	s_addc_u32 s3, s3, 0
	s_add_i32 s12, s12, s78
	v_lshl_add_u64 v[174:175], s[2:3], 0, v[0:1]
	s_mov_b32 m0, s12
	s_nop 0
	global_load_lds_dwordx4 v[174:175], off
	v_lshl_add_u64 v[174:175], s[2:3], 0, v[166:167]
	s_add_i32 m0, s12, 0x2000
	s_nop 0
	global_load_lds_dwordx4 v[174:175], off
	s_waitcnt vmcnt(6)
	s_nop 0
	s_waitcnt lgkmcnt(0)
	s_barrier
	s_waitcnt lgkmcnt(0)
	s_nop 0
	v_mfma_f32_16x16x32_bf16 v[94:97], v[98:101], v[114:117], v[94:97]
	v_mfma_f32_16x16x32_bf16 v[90:93], v[106:109], v[114:117], v[90:93]
	v_mfma_f32_16x16x32_bf16 v[86:89], v[98:101], v[122:125], v[86:89]
	v_mfma_f32_16x16x32_bf16 v[82:85], v[106:109], v[122:125], v[82:85]
	v_mfma_f32_16x16x32_bf16 v[78:81], v[98:101], v[186:189], v[78:81]
	v_mfma_f32_16x16x32_bf16 v[74:77], v[106:109], v[186:189], v[74:77]
	v_mfma_f32_16x16x32_bf16 v[70:73], v[98:101], v[194:197], v[70:73]
	v_mfma_f32_16x16x32_bf16 v[66:69], v[106:109], v[194:197], v[66:69]
	v_mfma_f32_16x16x32_bf16 v[94:97], v[102:105], v[118:121], v[94:97]
	v_mfma_f32_16x16x32_bf16 v[90:93], v[110:113], v[118:121], v[90:93]
	v_mfma_f32_16x16x32_bf16 v[86:89], v[102:105], v[126:129], v[86:89]
	v_mfma_f32_16x16x32_bf16 v[82:85], v[110:113], v[126:129], v[82:85]
	v_mfma_f32_16x16x32_bf16 v[78:81], v[102:105], v[190:193], v[78:81]
	v_mfma_f32_16x16x32_bf16 v[74:77], v[110:113], v[190:193], v[74:77]
	v_mfma_f32_16x16x32_bf16 v[70:73], v[102:105], v[198:201], v[70:73]
	v_mfma_f32_16x16x32_bf16 v[66:69], v[110:113], v[198:201], v[66:69]
	v_mfma_f32_16x16x32_bf16 v[30:33], v[226:229], v[114:117], v[30:33]
	v_mfma_f32_16x16x32_bf16 v[26:29], v[234:237], v[114:117], v[26:29]
	v_mfma_f32_16x16x32_bf16 v[22:25], v[226:229], v[122:125], v[22:25]
	v_mfma_f32_16x16x32_bf16 v[18:21], v[234:237], v[122:125], v[18:21]
	v_mfma_f32_16x16x32_bf16 v[14:17], v[226:229], v[186:189], v[14:17]
	v_mfma_f32_16x16x32_bf16 v[10:13], v[234:237], v[186:189], v[10:13]
	v_mfma_f32_16x16x32_bf16 v[6:9], v[226:229], v[194:197], v[6:9]
	v_mfma_f32_16x16x32_bf16 v[2:5], v[234:237], v[194:197], v[2:5]
	v_mfma_f32_16x16x32_bf16 v[30:33], v[230:233], v[118:121], v[30:33]
	v_mfma_f32_16x16x32_bf16 v[26:29], v[242:245], v[118:121], v[26:29]
	v_mfma_f32_16x16x32_bf16 v[22:25], v[230:233], v[126:129], v[22:25]
	v_mfma_f32_16x16x32_bf16 v[18:21], v[242:245], v[126:129], v[18:21]
	s_add_i32 s53, s53, 2
	s_add_u32 s34, s34, 0x100
	s_addc_u32 s35, s35, 0
	s_add_u32 s51, s51, 0x100
	s_addc_u32 s52, s52, 0
	s_cmp_gt_u32 s53, 13
	v_mfma_f32_16x16x32_bf16 v[14:17], v[230:233], v[190:193], v[14:17]
	v_mfma_f32_16x16x32_bf16 v[10:13], v[242:245], v[190:193], v[10:13]
	v_mfma_f32_16x16x32_bf16 v[6:9], v[230:233], v[198:201], v[6:9]
	v_mfma_f32_16x16x32_bf16 v[2:5], v[242:245], v[198:201], v[2:5]
	s_barrier
	s_cbranch_scc0 .LBB0_104

.LBB0_181:
	s_add_i32 s88, s44, -2
	s_add_u32 s34, s34, 0x80
	s_addc_u32 s35, s35, 0
	s_add_u32 s89, s42, 0x100
	v_mov_b32_e32 v2, 0
	s_addc_u32 s90, s43, 0
	s_mov_b32 s2, 0
	s_add_i32 s91, s2, 2
	s_add_u32 s12, s34, 0x80
	s_addc_u32 s3, s35, 0
	s_add_i32 s13, 0, 0x10000
	v_add_u32_e32 v142, s13, v183
	ds_read_b128 v[130:133], v142
	ds_read_b128 v[134:137], v142 offset:1024
	ds_read_b128 v[138:141], v142 offset:2048
	ds_read_b128 v[142:145], v142 offset:3072
	s_cmp_eq_u32 s88, s2
	s_cselect_b32 s2, s0, s12
	s_cselect_b32 s3, s1, s3
	s_cselect_b32 s43, s41, s90
	s_cselect_b32 s42, s40, s89
	v_lshl_add_u64 v[190:191], s[34:35], 0, v[174:175]
	s_add_i32 m0, s55, 0xc000
	ds_read_b128 v[146:149], v184
	ds_read_b128 v[150:153], v184 offset:1024
	ds_read_b128 v[154:157], v184 offset:2048
	ds_read_b128 v[158:161], v184 offset:3072
	ds_read_b128 v[162:165], v184 offset:4096
	ds_read_b128 v[166:169], v184 offset:5120
	ds_read_b128 v[178:181], v184 offset:6144
	ds_read_b128 v[186:189], v184 offset:7168
	global_load_lds_dwordx4 v[190:191], off
	v_lshl_add_u64 v[190:191], s[34:35], 0, v[176:177]
	s_add_i32 m0, s55, 0xe000
	s_nop 0
	global_load_lds_dwordx4 v[190:191], off
	s_add_i32 s92, 0, 0x14000
	s_add_i32 s12, s13, s54
	v_add_u32_e32 v185, s92, v183
	ds_read_b128 v[190:193], v185
	ds_read_b128 v[194:197], v185 offset:1024
	ds_read_b128 v[198:201], v185 offset:2048
	ds_read_b128 v[226:229], v185 offset:3072
	s_waitcnt lgkmcnt(0)
	s_barrier
	s_waitcnt lgkmcnt(0)
	v_mfma_f32_16x16x32_bf16 v[126:129], v[130:133], v[146:149], 0
	v_mfma_f32_16x16x32_bf16 v[122:125], v[138:141], v[146:149], 0
	v_mfma_f32_16x16x32_bf16 v[118:121], v[130:133], v[154:157], 0
	v_mfma_f32_16x16x32_bf16 v[114:117], v[138:141], v[154:157], 0
	v_mfma_f32_16x16x32_bf16 v[110:113], v[130:133], v[162:165], 0
	v_mfma_f32_16x16x32_bf16 v[106:109], v[138:141], v[162:165], 0
	v_mfma_f32_16x16x32_bf16 v[102:105], v[130:133], v[178:181], 0
	v_mfma_f32_16x16x32_bf16 v[98:101], v[138:141], v[178:181], 0
	v_mfma_f32_16x16x32_bf16 v[126:129], v[134:137], v[150:153], v[126:129]
	v_mfma_f32_16x16x32_bf16 v[122:125], v[142:145], v[150:153], v[122:125]
	v_mfma_f32_16x16x32_bf16 v[118:121], v[134:137], v[158:161], v[118:121]
	v_mfma_f32_16x16x32_bf16 v[114:117], v[142:145], v[158:161], v[114:117]
	v_mfma_f32_16x16x32_bf16 v[110:113], v[134:137], v[166:169], v[110:113]
	v_mfma_f32_16x16x32_bf16 v[106:109], v[142:145], v[166:169], v[106:109]
	v_mfma_f32_16x16x32_bf16 v[102:105], v[134:137], v[186:189], v[102:105]
	v_mfma_f32_16x16x32_bf16 v[98:101], v[142:145], v[186:189], v[98:101]
	v_mfma_f32_16x16x32_bf16 v[62:65], v[190:193], v[146:149], 0
	v_mfma_f32_16x16x32_bf16 v[58:61], v[198:201], v[146:149], 0
	v_mfma_f32_16x16x32_bf16 v[54:57], v[190:193], v[154:157], 0
	v_mfma_f32_16x16x32_bf16 v[50:53], v[198:201], v[154:157], 0
	v_mfma_f32_16x16x32_bf16 v[46:49], v[190:193], v[162:165], 0
	v_mfma_f32_16x16x32_bf16 v[42:45], v[198:201], v[162:165], 0
	v_mfma_f32_16x16x32_bf16 v[38:41], v[190:193], v[178:181], 0
	v_mfma_f32_16x16x32_bf16 v[34:37], v[198:201], v[178:181], 0
	v_mfma_f32_16x16x32_bf16 v[62:65], v[194:197], v[150:153], v[62:65]
	v_mfma_f32_16x16x32_bf16 v[58:61], v[226:229], v[150:153], v[58:61]
	v_mfma_f32_16x16x32_bf16 v[54:57], v[194:197], v[158:161], v[54:57]
	v_mfma_f32_16x16x32_bf16 v[50:53], v[226:229], v[158:161], v[50:53]
	s_mov_b32 m0, s55
	v_lshl_add_u64 v[234:235], s[2:3], 0, v[170:171]
	v_mfma_f32_16x16x32_bf16 v[46:49], v[194:197], v[166:169], v[46:49]
	v_mfma_f32_16x16x32_bf16 v[42:45], v[226:229], v[166:169], v[42:45]
	v_mfma_f32_16x16x32_bf16 v[38:41], v[194:197], v[186:189], v[38:41]
	v_mfma_f32_16x16x32_bf16 v[34:37], v[226:229], v[186:189], v[34:37]
	s_barrier
	ds_read_b128 v[146:149], v184 offset:16384
	ds_read_b128 v[150:153], v184 offset:17408
	ds_read_b128 v[154:157], v184 offset:18432
	ds_read_b128 v[158:161], v184 offset:19456
	ds_read_b128 v[162:165], v184 offset:20480
	ds_read_b128 v[166:169], v184 offset:21504
	ds_read_b128 v[178:181], v184 offset:22528
	ds_read_b128 v[186:189], v184 offset:23552
	global_load_lds_dwordx4 v[234:235], off
	v_lshl_add_u64 v[236:237], s[2:3], 0, v[172:173]
	s_mov_b32 m0, s58
	s_nop 0
	global_load_lds_dwordx4 v[236:237], off
	v_lshl_add_u64 v[230:231], s[42:43], 0, v[170:171]
	s_mov_b32 m0, s12
	s_nop 0
	global_load_lds_dwordx4 v[230:231], off
	v_lshl_add_u64 v[232:233], s[42:43], 0, v[172:173]
	s_add_i32 m0, s12, 0x2000
	s_nop 0
	global_load_lds_dwordx4 v[232:233], off
	s_add_u32 s12, s42, s18
	s_addc_u32 s13, s43, 0
	s_add_i32 s42, s92, s54
	v_lshl_add_u64 v[242:243], s[12:13], 0, v[170:171]
	s_mov_b32 m0, s42
	v_lshl_add_u64 v[244:245], s[12:13], 0, v[172:173]
	global_load_lds_dwordx4 v[242:243], off
	s_add_i32 m0, s42, 0x2000
	s_nop 0
	global_load_lds_dwordx4 v[244:245], off
	s_waitcnt vmcnt(6)
	s_nop 0
	s_waitcnt lgkmcnt(0)
	s_barrier
	s_waitcnt lgkmcnt(0)
	s_nop 0
	v_mfma_f32_16x16x32_bf16 v[94:97], v[130:133], v[146:149], 0
	v_mfma_f32_16x16x32_bf16 v[90:93], v[138:141], v[146:149], 0
	v_mfma_f32_16x16x32_bf16 v[86:89], v[130:133], v[154:157], 0
	v_mfma_f32_16x16x32_bf16 v[82:85], v[138:141], v[154:157], 0
	v_mfma_f32_16x16x32_bf16 v[78:81], v[130:133], v[162:165], 0
	v_mfma_f32_16x16x32_bf16 v[74:77], v[138:141], v[162:165], 0
	v_mfma_f32_16x16x32_bf16 v[70:73], v[130:133], v[178:181], 0
	v_mfma_f32_16x16x32_bf16 v[66:69], v[138:141], v[178:181], 0
	v_mfma_f32_16x16x32_bf16 v[94:97], v[134:137], v[150:153], v[94:97]
	v_mfma_f32_16x16x32_bf16 v[90:93], v[142:145], v[150:153], v[90:93]
	v_mfma_f32_16x16x32_bf16 v[86:89], v[134:137], v[158:161], v[86:89]
	v_mfma_f32_16x16x32_bf16 v[82:85], v[142:145], v[158:161], v[82:85]
	v_mfma_f32_16x16x32_bf16 v[78:81], v[134:137], v[166:169], v[78:81]
	v_mfma_f32_16x16x32_bf16 v[74:77], v[142:145], v[166:169], v[74:77]
	v_mfma_f32_16x16x32_bf16 v[70:73], v[134:137], v[186:189], v[70:73]
	v_mfma_f32_16x16x32_bf16 v[66:69], v[142:145], v[186:189], v[66:69]
	v_mfma_f32_16x16x32_bf16 v[30:33], v[190:193], v[146:149], 0
	v_mfma_f32_16x16x32_bf16 v[26:29], v[198:201], v[146:149], 0
	v_mfma_f32_16x16x32_bf16 v[22:25], v[190:193], v[154:157], 0
	v_mfma_f32_16x16x32_bf16 v[18:21], v[198:201], v[154:157], 0
	v_mfma_f32_16x16x32_bf16 v[14:17], v[190:193], v[162:165], 0
	v_mfma_f32_16x16x32_bf16 v[10:13], v[198:201], v[162:165], 0
	v_mfma_f32_16x16x32_bf16 v[6:9], v[190:193], v[178:181], 0
	v_mfma_f32_16x16x32_bf16 v[2:5], v[198:201], v[178:181], 0
	v_mfma_f32_16x16x32_bf16 v[30:33], v[194:197], v[150:153], v[30:33]
	v_mfma_f32_16x16x32_bf16 v[26:29], v[226:229], v[150:153], v[26:29]
	v_mfma_f32_16x16x32_bf16 v[22:25], v[194:197], v[158:161], v[22:25]
	v_mfma_f32_16x16x32_bf16 v[18:21], v[226:229], v[158:161], v[18:21]
	s_add_i32 s12, 0, 0x18000
	v_add_u32_e32 v142, s12, v183
	v_mfma_f32_16x16x32_bf16 v[14:17], v[194:197], v[166:169], v[14:17]
	v_mfma_f32_16x16x32_bf16 v[10:13], v[226:229], v[166:169], v[10:13]
	v_mfma_f32_16x16x32_bf16 v[6:9], v[194:197], v[186:189], v[6:9]
	v_mfma_f32_16x16x32_bf16 v[2:5], v[226:229], v[186:189], v[2:5]
	s_barrier
	ds_read_b128 v[130:133], v142
	ds_read_b128 v[134:137], v142 offset:1024
	ds_read_b128 v[138:141], v142 offset:2048
	ds_read_b128 v[142:145], v142 offset:3072
	s_add_u32 s2, s2, s18
	s_addc_u32 s3, s3, 0
	s_mov_b32 m0, s59
	v_lshl_add_u64 v[190:191], s[2:3], 0, v[170:171]
	ds_read_b128 v[146:149], v184 offset:32768
	ds_read_b128 v[150:153], v184 offset:33792
	ds_read_b128 v[154:157], v184 offset:34816
	ds_read_b128 v[158:161], v184 offset:35840
	ds_read_b128 v[162:165], v184 offset:36864
	ds_read_b128 v[166:169], v184 offset:37888
	ds_read_b128 v[178:181], v184 offset:38912
	ds_read_b128 v[186:189], v184 offset:39936
	global_load_lds_dwordx4 v[190:191], off
	v_lshl_add_u64 v[190:191], s[2:3], 0, v[172:173]
	s_mov_b32 m0, s77
	s_nop 0
	global_load_lds_dwordx4 v[190:191], off
	s_add_i32 s2, 0, 0x1c000
	s_add_i32 s3, s12, s54
	v_add_u32_e32 v185, s2, v183
	ds_read_b128 v[190:193], v185
	ds_read_b128 v[194:197], v185 offset:1024
	ds_read_b128 v[198:201], v185 offset:2048
	ds_read_b128 v[226:229], v185 offset:3072
	s_waitcnt lgkmcnt(0)
	s_barrier
	s_waitcnt lgkmcnt(0)
	v_mfma_f32_16x16x32_bf16 v[126:129], v[130:133], v[146:149], v[126:129]
	v_mfma_f32_16x16x32_bf16 v[122:125], v[138:141], v[146:149], v[122:125]
	v_mfma_f32_16x16x32_bf16 v[118:121], v[130:133], v[154:157], v[118:121]
	v_mfma_f32_16x16x32_bf16 v[114:117], v[138:141], v[154:157], v[114:117]
	v_mfma_f32_16x16x32_bf16 v[110:113], v[130:133], v[162:165], v[110:113]
	v_mfma_f32_16x16x32_bf16 v[106:109], v[138:141], v[162:165], v[106:109]
	v_mfma_f32_16x16x32_bf16 v[102:105], v[130:133], v[178:181], v[102:105]
	v_mfma_f32_16x16x32_bf16 v[98:101], v[138:141], v[178:181], v[98:101]
	v_mfma_f32_16x16x32_bf16 v[126:129], v[134:137], v[150:153], v[126:129]
	v_mfma_f32_16x16x32_bf16 v[122:125], v[142:145], v[150:153], v[122:125]
	v_mfma_f32_16x16x32_bf16 v[118:121], v[134:137], v[158:161], v[118:121]
	v_mfma_f32_16x16x32_bf16 v[114:117], v[142:145], v[158:161], v[114:117]
	v_mfma_f32_16x16x32_bf16 v[110:113], v[134:137], v[166:169], v[110:113]
	v_mfma_f32_16x16x32_bf16 v[106:109], v[142:145], v[166:169], v[106:109]
	v_mfma_f32_16x16x32_bf16 v[102:105], v[134:137], v[186:189], v[102:105]
	v_mfma_f32_16x16x32_bf16 v[98:101], v[142:145], v[186:189], v[98:101]
	v_mfma_f32_16x16x32_bf16 v[62:65], v[190:193], v[146:149], v[62:65]
	v_mfma_f32_16x16x32_bf16 v[58:61], v[198:201], v[146:149], v[58:61]
	v_mfma_f32_16x16x32_bf16 v[54:57], v[190:193], v[154:157], v[54:57]
	v_mfma_f32_16x16x32_bf16 v[50:53], v[198:201], v[154:157], v[50:53]
	v_mfma_f32_16x16x32_bf16 v[46:49], v[190:193], v[162:165], v[46:49]
	v_mfma_f32_16x16x32_bf16 v[42:45], v[198:201], v[162:165], v[42:45]
	v_mfma_f32_16x16x32_bf16 v[38:41], v[190:193], v[178:181], v[38:41]
	v_mfma_f32_16x16x32_bf16 v[34:37], v[198:201], v[178:181], v[34:37]
	v_mfma_f32_16x16x32_bf16 v[62:65], v[194:197], v[150:153], v[62:65]
	v_mfma_f32_16x16x32_bf16 v[58:61], v[226:229], v[150:153], v[58:61]
	v_mfma_f32_16x16x32_bf16 v[54:57], v[194:197], v[158:161], v[54:57]
	v_mfma_f32_16x16x32_bf16 v[50:53], v[226:229], v[158:161], v[50:53]
	s_mov_b32 m0, s80
	v_lshl_add_u64 v[234:235], v[234:235], 0, s[20:21]
	v_mfma_f32_16x16x32_bf16 v[46:49], v[194:197], v[166:169], v[46:49]
	v_mfma_f32_16x16x32_bf16 v[42:45], v[226:229], v[166:169], v[42:45]
	v_mfma_f32_16x16x32_bf16 v[38:41], v[194:197], v[186:189], v[38:41]
	v_mfma_f32_16x16x32_bf16 v[34:37], v[226:229], v[186:189], v[34:37]
	s_barrier
	ds_read_b128 v[146:149], v184 offset:49152
	ds_read_b128 v[150:153], v184 offset:50176
	ds_read_b128 v[154:157], v184 offset:51200
	ds_read_b128 v[158:161], v184 offset:52224
	ds_read_b128 v[162:165], v184 offset:53248
	ds_read_b128 v[166:169], v184 offset:54272
	ds_read_b128 v[178:181], v184 offset:55296
	ds_read_b128 v[186:189], v184 offset:56320
	global_load_lds_dwordx4 v[234:235], off
	v_lshl_add_u64 v[236:237], v[236:237], 0, s[20:21]
	s_mov_b32 m0, s81
	s_nop 0
	global_load_lds_dwordx4 v[236:237], off
	v_lshl_add_u64 v[230:231], v[230:231], 0, s[20:21]
	s_mov_b32 m0, s3
	s_nop 0
	global_load_lds_dwordx4 v[230:231], off
	v_lshl_add_u64 v[230:231], v[232:233], 0, s[20:21]
	s_add_i32 m0, s3, 0x2000
	s_nop 0
	global_load_lds_dwordx4 v[230:231], off
	s_add_i32 s2, s2, s54
	v_lshl_add_u64 v[242:243], v[242:243], 0, s[20:21]
	s_mov_b32 m0, s2
	s_nop 0
	global_load_lds_dwordx4 v[242:243], off
	v_lshl_add_u64 v[244:245], v[244:245], 0, s[20:21]
	s_add_i32 m0, s2, 0x2000
	s_nop 0
	global_load_lds_dwordx4 v[244:245], off
	s_waitcnt vmcnt(6)
	s_nop 0
	s_waitcnt lgkmcnt(0)
	s_barrier
	s_waitcnt lgkmcnt(0)
	v_mfma_f32_16x16x32_bf16 v[94:97], v[130:133], v[146:149], v[94:97]
	v_mfma_f32_16x16x32_bf16 v[90:93], v[138:141], v[146:149], v[90:93]
	v_mfma_f32_16x16x32_bf16 v[86:89], v[130:133], v[154:157], v[86:89]
	v_mfma_f32_16x16x32_bf16 v[82:85], v[138:141], v[154:157], v[82:85]
	v_mfma_f32_16x16x32_bf16 v[78:81], v[130:133], v[162:165], v[78:81]
	v_mfma_f32_16x16x32_bf16 v[74:77], v[138:141], v[162:165], v[74:77]
	v_mfma_f32_16x16x32_bf16 v[70:73], v[130:133], v[178:181], v[70:73]
	v_mfma_f32_16x16x32_bf16 v[66:69], v[138:141], v[178:181], v[66:69]
	v_mfma_f32_16x16x32_bf16 v[94:97], v[134:137], v[150:153], v[94:97]
	v_mfma_f32_16x16x32_bf16 v[90:93], v[142:145], v[150:153], v[90:93]
	v_mfma_f32_16x16x32_bf16 v[86:89], v[134:137], v[158:161], v[86:89]
	v_mfma_f32_16x16x32_bf16 v[82:85], v[142:145], v[158:161], v[82:85]
	v_mfma_f32_16x16x32_bf16 v[78:81], v[134:137], v[166:169], v[78:81]
	v_mfma_f32_16x16x32_bf16 v[74:77], v[142:145], v[166:169], v[74:77]
	v_mfma_f32_16x16x32_bf16 v[70:73], v[134:137], v[186:189], v[70:73]
	v_mfma_f32_16x16x32_bf16 v[66:69], v[142:145], v[186:189], v[66:69]
	v_mfma_f32_16x16x32_bf16 v[30:33], v[190:193], v[146:149], v[30:33]
	v_mfma_f32_16x16x32_bf16 v[26:29], v[198:201], v[146:149], v[26:29]
	v_mfma_f32_16x16x32_bf16 v[22:25], v[190:193], v[154:157], v[22:25]
	v_mfma_f32_16x16x32_bf16 v[18:21], v[198:201], v[154:157], v[18:21]
	v_mfma_f32_16x16x32_bf16 v[14:17], v[190:193], v[162:165], v[14:17]
	v_mfma_f32_16x16x32_bf16 v[10:13], v[198:201], v[162:165], v[10:13]
	v_mfma_f32_16x16x32_bf16 v[6:9], v[190:193], v[178:181], v[6:9]
	v_mfma_f32_16x16x32_bf16 v[2:5], v[198:201], v[178:181], v[2:5]
	v_mfma_f32_16x16x32_bf16 v[30:33], v[194:197], v[150:153], v[30:33]
	v_mfma_f32_16x16x32_bf16 v[26:29], v[226:229], v[150:153], v[26:29]
	v_mfma_f32_16x16x32_bf16 v[22:25], v[194:197], v[158:161], v[22:25]
	v_mfma_f32_16x16x32_bf16 v[18:21], v[226:229], v[158:161], v[18:21]
	s_add_u32 s34, s34, 0x100
	s_addc_u32 s35, s35, 0
	s_add_u32 s89, s89, 0x100
	s_addc_u32 s90, s90, 0
	s_cmp_ge_i32 s91, s44
	s_mov_b32 s2, s91
	v_mfma_f32_16x16x32_bf16 v[14:17], v[194:197], v[166:169], v[14:17]
	v_mfma_f32_16x16x32_bf16 v[10:13], v[226:229], v[166:169], v[10:13]
	v_mfma_f32_16x16x32_bf16 v[6:9], v[194:197], v[186:189], v[6:9]
	v_mfma_f32_16x16x32_bf16 v[2:5], v[226:229], v[186:189], v[2:5]
	s_barrier
	s_cbranch_scc1 .Lpeel_x_1
.LBB0_182:
	s_add_i32 s91, s2, 2
	s_add_u32 s12, s34, 0x80
	s_addc_u32 s3, s35, 0
	s_add_i32 s13, 0, 0x10000
	v_add_u32_e32 v142, s13, v183
	ds_read_b128 v[130:133], v142
	ds_read_b128 v[134:137], v142 offset:1024
	ds_read_b128 v[138:141], v142 offset:2048
	ds_read_b128 v[142:145], v142 offset:3072
	s_cmp_eq_u32 s88, s2
	s_cselect_b32 s2, s0, s12
	s_cselect_b32 s3, s1, s3
	s_cselect_b32 s43, s41, s90
	s_cselect_b32 s42, s40, s89
	v_lshl_add_u64 v[190:191], s[34:35], 0, v[174:175]
	s_add_i32 m0, s55, 0xc000
	ds_read_b128 v[146:149], v184
	ds_read_b128 v[150:153], v184 offset:1024
	ds_read_b128 v[154:157], v184 offset:2048
	ds_read_b128 v[158:161], v184 offset:3072
	ds_read_b128 v[162:165], v184 offset:4096
	ds_read_b128 v[166:169], v184 offset:5120
	ds_read_b128 v[178:181], v184 offset:6144
	ds_read_b128 v[186:189], v184 offset:7168
	global_load_lds_dwordx4 v[190:191], off
	v_lshl_add_u64 v[190:191], s[34:35], 0, v[176:177]
	s_add_i32 m0, s55, 0xe000
	s_nop 0
	global_load_lds_dwordx4 v[190:191], off
	s_add_i32 s92, 0, 0x14000
	s_add_i32 s12, s13, s54
	v_add_u32_e32 v185, s92, v183
	ds_read_b128 v[190:193], v185
	ds_read_b128 v[194:197], v185 offset:1024
	ds_read_b128 v[198:201], v185 offset:2048
	ds_read_b128 v[226:229], v185 offset:3072
	s_waitcnt lgkmcnt(0)
	s_barrier
	s_waitcnt lgkmcnt(0)
	v_mfma_f32_16x16x32_bf16 v[126:129], v[130:133], v[146:149], v[126:129]
	v_mfma_f32_16x16x32_bf16 v[122:125], v[138:141], v[146:149], v[122:125]
	v_mfma_f32_16x16x32_bf16 v[118:121], v[130:133], v[154:157], v[118:121]
	v_mfma_f32_16x16x32_bf16 v[114:117], v[138:141], v[154:157], v[114:117]
	v_mfma_f32_16x16x32_bf16 v[110:113], v[130:133], v[162:165], v[110:113]
	v_mfma_f32_16x16x32_bf16 v[106:109], v[138:141], v[162:165], v[106:109]
	v_mfma_f32_16x16x32_bf16 v[102:105], v[130:133], v[178:181], v[102:105]
	v_mfma_f32_16x16x32_bf16 v[98:101], v[138:141], v[178:181], v[98:101]
	v_mfma_f32_16x16x32_bf16 v[126:129], v[134:137], v[150:153], v[126:129]
	v_mfma_f32_16x16x32_bf16 v[122:125], v[142:145], v[150:153], v[122:125]
	v_mfma_f32_16x16x32_bf16 v[118:121], v[134:137], v[158:161], v[118:121]
	v_mfma_f32_16x16x32_bf16 v[114:117], v[142:145], v[158:161], v[114:117]
	v_mfma_f32_16x16x32_bf16 v[110:113], v[134:137], v[166:169], v[110:113]
	v_mfma_f32_16x16x32_bf16 v[106:109], v[142:145], v[166:169], v[106:109]
	v_mfma_f32_16x16x32_bf16 v[102:105], v[134:137], v[186:189], v[102:105]
	v_mfma_f32_16x16x32_bf16 v[98:101], v[142:145], v[186:189], v[98:101]
	v_mfma_f32_16x16x32_bf16 v[62:65], v[190:193], v[146:149], v[62:65]
	v_mfma_f32_16x16x32_bf16 v[58:61], v[198:201], v[146:149], v[58:61]
	v_mfma_f32_16x16x32_bf16 v[54:57], v[190:193], v[154:157], v[54:57]
	v_mfma_f32_16x16x32_bf16 v[50:53], v[198:201], v[154:157], v[50:53]
	v_mfma_f32_16x16x32_bf16 v[46:49], v[190:193], v[162:165], v[46:49]
	v_mfma_f32_16x16x32_bf16 v[42:45], v[198:201], v[162:165], v[42:45]
	v_mfma_f32_16x16x32_bf16 v[38:41], v[190:193], v[178:181], v[38:41]
	v_mfma_f32_16x16x32_bf16 v[34:37], v[198:201], v[178:181], v[34:37]
	v_mfma_f32_16x16x32_bf16 v[62:65], v[194:197], v[150:153], v[62:65]
	v_mfma_f32_16x16x32_bf16 v[58:61], v[226:229], v[150:153], v[58:61]
	v_mfma_f32_16x16x32_bf16 v[54:57], v[194:197], v[158:161], v[54:57]
	v_mfma_f32_16x16x32_bf16 v[50:53], v[226:229], v[158:161], v[50:53]
	s_mov_b32 m0, s55
	v_lshl_add_u64 v[234:235], s[2:3], 0, v[170:171]
	v_mfma_f32_16x16x32_bf16 v[46:49], v[194:197], v[166:169], v[46:49]
	v_mfma_f32_16x16x32_bf16 v[42:45], v[226:229], v[166:169], v[42:45]
	v_mfma_f32_16x16x32_bf16 v[38:41], v[194:197], v[186:189], v[38:41]
	v_mfma_f32_16x16x32_bf16 v[34:37], v[226:229], v[186:189], v[34:37]
	s_barrier
	ds_read_b128 v[146:149], v184 offset:16384
	ds_read_b128 v[150:153], v184 offset:17408
	ds_read_b128 v[154:157], v184 offset:18432
	ds_read_b128 v[158:161], v184 offset:19456
	ds_read_b128 v[162:165], v184 offset:20480
	ds_read_b128 v[166:169], v184 offset:21504
	ds_read_b128 v[178:181], v184 offset:22528
	ds_read_b128 v[186:189], v184 offset:23552
	global_load_lds_dwordx4 v[234:235], off
	v_lshl_add_u64 v[236:237], s[2:3], 0, v[172:173]
	s_mov_b32 m0, s58
	s_nop 0
	global_load_lds_dwordx4 v[236:237], off
	v_lshl_add_u64 v[230:231], s[42:43], 0, v[170:171]
	s_mov_b32 m0, s12
	s_nop 0
	global_load_lds_dwordx4 v[230:231], off
	v_lshl_add_u64 v[232:233], s[42:43], 0, v[172:173]
	s_add_i32 m0, s12, 0x2000
	s_nop 0
	global_load_lds_dwordx4 v[232:233], off
	s_add_u32 s12, s42, s18
	s_addc_u32 s13, s43, 0
	s_add_i32 s42, s92, s54
	v_lshl_add_u64 v[242:243], s[12:13], 0, v[170:171]
	s_mov_b32 m0, s42
	v_lshl_add_u64 v[244:245], s[12:13], 0, v[172:173]
	global_load_lds_dwordx4 v[242:243], off
	s_add_i32 m0, s42, 0x2000
	s_nop 0
	global_load_lds_dwordx4 v[244:245], off
	s_waitcnt vmcnt(6)
	s_nop 0
	s_waitcnt lgkmcnt(0)
	s_barrier
	s_waitcnt lgkmcnt(0)
	s_nop 0
	v_mfma_f32_16x16x32_bf16 v[94:97], v[130:133], v[146:149], v[94:97]
	v_mfma_f32_16x16x32_bf16 v[90:93], v[138:141], v[146:149], v[90:93]
	v_mfma_f32_16x16x32_bf16 v[86:89], v[130:133], v[154:157], v[86:89]
	v_mfma_f32_16x16x32_bf16 v[82:85], v[138:141], v[154:157], v[82:85]
	v_mfma_f32_16x16x32_bf16 v[78:81], v[130:133], v[162:165], v[78:81]
	v_mfma_f32_16x16x32_bf16 v[74:77], v[138:141], v[162:165], v[74:77]
	v_mfma_f32_16x16x32_bf16 v[70:73], v[130:133], v[178:181], v[70:73]
	v_mfma_f32_16x16x32_bf16 v[66:69], v[138:141], v[178:181], v[66:69]
	v_mfma_f32_16x16x32_bf16 v[94:97], v[134:137], v[150:153], v[94:97]
	v_mfma_f32_16x16x32_bf16 v[90:93], v[142:145], v[150:153], v[90:93]
	v_mfma_f32_16x16x32_bf16 v[86:89], v[134:137], v[158:161], v[86:89]
	v_mfma_f32_16x16x32_bf16 v[82:85], v[142:145], v[158:161], v[82:85]
	v_mfma_f32_16x16x32_bf16 v[78:81], v[134:137], v[166:169], v[78:81]
	v_mfma_f32_16x16x32_bf16 v[74:77], v[142:145], v[166:169], v[74:77]
	v_mfma_f32_16x16x32_bf16 v[70:73], v[134:137], v[186:189], v[70:73]
	v_mfma_f32_16x16x32_bf16 v[66:69], v[142:145], v[186:189], v[66:69]
	v_mfma_f32_16x16x32_bf16 v[30:33], v[190:193], v[146:149], v[30:33]
	v_mfma_f32_16x16x32_bf16 v[26:29], v[198:201], v[146:149], v[26:29]
	v_mfma_f32_16x16x32_bf16 v[22:25], v[190:193], v[154:157], v[22:25]
	v_mfma_f32_16x16x32_bf16 v[18:21], v[198:201], v[154:157], v[18:21]
	v_mfma_f32_16x16x32_bf16 v[14:17], v[190:193], v[162:165], v[14:17]
	v_mfma_f32_16x16x32_bf16 v[10:13], v[198:201], v[162:165], v[10:13]
	v_mfma_f32_16x16x32_bf16 v[6:9], v[190:193], v[178:181], v[6:9]
	v_mfma_f32_16x16x32_bf16 v[2:5], v[198:201], v[178:181], v[2:5]
	v_mfma_f32_16x16x32_bf16 v[30:33], v[194:197], v[150:153], v[30:33]
	v_mfma_f32_16x16x32_bf16 v[26:29], v[226:229], v[150:153], v[26:29]
	v_mfma_f32_16x16x32_bf16 v[22:25], v[194:197], v[158:161], v[22:25]
	v_mfma_f32_16x16x32_bf16 v[18:21], v[226:229], v[158:161], v[18:21]
	s_add_i32 s12, 0, 0x18000
	v_add_u32_e32 v142, s12, v183
	v_mfma_f32_16x16x32_bf16 v[14:17], v[194:197], v[166:169], v[14:17]
	v_mfma_f32_16x16x32_bf16 v[10:13], v[226:229], v[166:169], v[10:13]
	v_mfma_f32_16x16x32_bf16 v[6:9], v[194:197], v[186:189], v[6:9]
	v_mfma_f32_16x16x32_bf16 v[2:5], v[226:229], v[186:189], v[2:5]
	s_barrier
	ds_read_b128 v[130:133], v142
	ds_read_b128 v[134:137], v142 offset:1024
	ds_read_b128 v[138:141], v142 offset:2048
	ds_read_b128 v[142:145], v142 offset:3072
	s_add_u32 s2, s2, s18
	s_addc_u32 s3, s3, 0
	s_mov_b32 m0, s59
	v_lshl_add_u64 v[190:191], s[2:3], 0, v[170:171]
	ds_read_b128 v[146:149], v184 offset:32768
	ds_read_b128 v[150:153], v184 offset:33792
	ds_read_b128 v[154:157], v184 offset:34816
	ds_read_b128 v[158:161], v184 offset:35840
	ds_read_b128 v[162:165], v184 offset:36864
	ds_read_b128 v[166:169], v184 offset:37888
	ds_read_b128 v[178:181], v184 offset:38912
	ds_read_b128 v[186:189], v184 offset:39936
	global_load_lds_dwordx4 v[190:191], off
	v_lshl_add_u64 v[190:191], s[2:3], 0, v[172:173]
	s_mov_b32 m0, s77
	s_nop 0
	global_load_lds_dwordx4 v[190:191], off
	s_add_i32 s2, 0, 0x1c000
	s_add_i32 s3, s12, s54
	v_add_u32_e32 v185, s2, v183
	ds_read_b128 v[190:193], v185
	ds_read_b128 v[194:197], v185 offset:1024
	ds_read_b128 v[198:201], v185 offset:2048
	ds_read_b128 v[226:229], v185 offset:3072
	s_waitcnt lgkmcnt(0)
	s_barrier
	s_waitcnt lgkmcnt(0)
	v_mfma_f32_16x16x32_bf16 v[126:129], v[130:133], v[146:149], v[126:129]
	v_mfma_f32_16x16x32_bf16 v[122:125], v[138:141], v[146:149], v[122:125]
	v_mfma_f32_16x16x32_bf16 v[118:121], v[130:133], v[154:157], v[118:121]
	v_mfma_f32_16x16x32_bf16 v[114:117], v[138:141], v[154:157], v[114:117]
	v_mfma_f32_16x16x32_bf16 v[110:113], v[130:133], v[162:165], v[110:113]
	v_mfma_f32_16x16x32_bf16 v[106:109], v[138:141], v[162:165], v[106:109]
	v_mfma_f32_16x16x32_bf16 v[102:105], v[130:133], v[178:181], v[102:105]
	v_mfma_f32_16x16x32_bf16 v[98:101], v[138:141], v[178:181], v[98:101]
	v_mfma_f32_16x16x32_bf16 v[126:129], v[134:137], v[150:153], v[126:129]
	v_mfma_f32_16x16x32_bf16 v[122:125], v[142:145], v[150:153], v[122:125]
	v_mfma_f32_16x16x32_bf16 v[118:121], v[134:137], v[158:161], v[118:121]
	v_mfma_f32_16x16x32_bf16 v[114:117], v[142:145], v[158:161], v[114:117]
	v_mfma_f32_16x16x32_bf16 v[110:113], v[134:137], v[166:169], v[110:113]
	v_mfma_f32_16x16x32_bf16 v[106:109], v[142:145], v[166:169], v[106:109]
	v_mfma_f32_16x16x32_bf16 v[102:105], v[134:137], v[186:189], v[102:105]
	v_mfma_f32_16x16x32_bf16 v[98:101], v[142:145], v[186:189], v[98:101]
	v_mfma_f32_16x16x32_bf16 v[62:65], v[190:193], v[146:149], v[62:65]
	v_mfma_f32_16x16x32_bf16 v[58:61], v[198:201], v[146:149], v[58:61]
	v_mfma_f32_16x16x32_bf16 v[54:57], v[190:193], v[154:157], v[54:57]
	v_mfma_f32_16x16x32_bf16 v[50:53], v[198:201], v[154:157], v[50:53]
	v_mfma_f32_16x16x32_bf16 v[46:49], v[190:193], v[162:165], v[46:49]
	v_mfma_f32_16x16x32_bf16 v[42:45], v[198:201], v[162:165], v[42:45]
	v_mfma_f32_16x16x32_bf16 v[38:41], v[190:193], v[178:181], v[38:41]
	v_mfma_f32_16x16x32_bf16 v[34:37], v[198:201], v[178:181], v[34:37]
	v_mfma_f32_16x16x32_bf16 v[62:65], v[194:197], v[150:153], v[62:65]
	v_mfma_f32_16x16x32_bf16 v[58:61], v[226:229], v[150:153], v[58:61]
	v_mfma_f32_16x16x32_bf16 v[54:57], v[194:197], v[158:161], v[54:57]
	v_mfma_f32_16x16x32_bf16 v[50:53], v[226:229], v[158:161], v[50:53]
	s_mov_b32 m0, s80
	v_lshl_add_u64 v[234:235], v[234:235], 0, s[20:21]
	v_mfma_f32_16x16x32_bf16 v[46:49], v[194:197], v[166:169], v[46:49]
	v_mfma_f32_16x16x32_bf16 v[42:45], v[226:229], v[166:169], v[42:45]
	v_mfma_f32_16x16x32_bf16 v[38:41], v[194:197], v[186:189], v[38:41]
	v_mfma_f32_16x16x32_bf16 v[34:37], v[226:229], v[186:189], v[34:37]
	s_barrier
	ds_read_b128 v[146:149], v184 offset:49152
	ds_read_b128 v[150:153], v184 offset:50176
	ds_read_b128 v[154:157], v184 offset:51200
	ds_read_b128 v[158:161], v184 offset:52224
	ds_read_b128 v[162:165], v184 offset:53248
	ds_read_b128 v[166:169], v184 offset:54272
	ds_read_b128 v[178:181], v184 offset:55296
	ds_read_b128 v[186:189], v184 offset:56320
	global_load_lds_dwordx4 v[234:235], off
	v_lshl_add_u64 v[236:237], v[236:237], 0, s[20:21]
	s_mov_b32 m0, s81
	s_nop 0
	global_load_lds_dwordx4 v[236:237], off
	v_lshl_add_u64 v[230:231], v[230:231], 0, s[20:21]
	s_mov_b32 m0, s3
	s_nop 0
	global_load_lds_dwordx4 v[230:231], off
	v_lshl_add_u64 v[230:231], v[232:233], 0, s[20:21]
	s_add_i32 m0, s3, 0x2000
	s_nop 0
	global_load_lds_dwordx4 v[230:231], off
	s_add_i32 s2, s2, s54
	v_lshl_add_u64 v[242:243], v[242:243], 0, s[20:21]
	s_mov_b32 m0, s2
	s_nop 0
	global_load_lds_dwordx4 v[242:243], off
	v_lshl_add_u64 v[244:245], v[244:245], 0, s[20:21]
	s_add_i32 m0, s2, 0x2000
	s_nop 0
	global_load_lds_dwordx4 v[244:245], off
	s_waitcnt vmcnt(6)
	s_nop 0
	s_waitcnt lgkmcnt(0)
	s_barrier
	s_waitcnt lgkmcnt(0)
	v_mfma_f32_16x16x32_bf16 v[94:97], v[130:133], v[146:149], v[94:97]
	v_mfma_f32_16x16x32_bf16 v[90:93], v[138:141], v[146:149], v[90:93]
	v_mfma_f32_16x16x32_bf16 v[86:89], v[130:133], v[154:157], v[86:89]
	v_mfma_f32_16x16x32_bf16 v[82:85], v[138:141], v[154:157], v[82:85]
	v_mfma_f32_16x16x32_bf16 v[78:81], v[130:133], v[162:165], v[78:81]
	v_mfma_f32_16x16x32_bf16 v[74:77], v[138:141], v[162:165], v[74:77]
	v_mfma_f32_16x16x32_bf16 v[70:73], v[130:133], v[178:181], v[70:73]
	v_mfma_f32_16x16x32_bf16 v[66:69], v[138:141], v[178:181], v[66:69]
	v_mfma_f32_16x16x32_bf16 v[94:97], v[134:137], v[150:153], v[94:97]
	v_mfma_f32_16x16x32_bf16 v[90:93], v[142:145], v[150:153], v[90:93]
	v_mfma_f32_16x16x32_bf16 v[86:89], v[134:137], v[158:161], v[86:89]
	v_mfma_f32_16x16x32_bf16 v[82:85], v[142:145], v[158:161], v[82:85]
	v_mfma_f32_16x16x32_bf16 v[78:81], v[134:137], v[166:169], v[78:81]
	v_mfma_f32_16x16x32_bf16 v[74:77], v[142:145], v[166:169], v[74:77]
	v_mfma_f32_16x16x32_bf16 v[70:73], v[134:137], v[186:189], v[70:73]
	v_mfma_f32_16x16x32_bf16 v[66:69], v[142:145], v[186:189], v[66:69]
	v_mfma_f32_16x16x32_bf16 v[30:33], v[190:193], v[146:149], v[30:33]
	v_mfma_f32_16x16x32_bf16 v[26:29], v[198:201], v[146:149], v[26:29]
	v_mfma_f32_16x16x32_bf16 v[22:25], v[190:193], v[154:157], v[22:25]
	v_mfma_f32_16x16x32_bf16 v[18:21], v[198:201], v[154:157], v[18:21]
	v_mfma_f32_16x16x32_bf16 v[14:17], v[190:193], v[162:165], v[14:17]
	v_mfma_f32_16x16x32_bf16 v[10:13], v[198:201], v[162:165], v[10:13]
	v_mfma_f32_16x16x32_bf16 v[6:9], v[190:193], v[178:181], v[6:9]
	v_mfma_f32_16x16x32_bf16 v[2:5], v[198:201], v[178:181], v[2:5]
	v_mfma_f32_16x16x32_bf16 v[30:33], v[194:197], v[150:153], v[30:33]
	v_mfma_f32_16x16x32_bf16 v[26:29], v[226:229], v[150:153], v[26:29]
	v_mfma_f32_16x16x32_bf16 v[22:25], v[194:197], v[158:161], v[22:25]
	v_mfma_f32_16x16x32_bf16 v[18:21], v[226:229], v[158:161], v[18:21]
	s_add_u32 s34, s34, 0x100
	s_addc_u32 s35, s35, 0
	s_add_u32 s89, s89, 0x100
	s_addc_u32 s90, s90, 0
	s_cmp_ge_i32 s91, s44
	s_mov_b32 s2, s91
	v_mfma_f32_16x16x32_bf16 v[14:17], v[194:197], v[166:169], v[14:17]
	v_mfma_f32_16x16x32_bf16 v[10:13], v[226:229], v[166:169], v[10:13]
	v_mfma_f32_16x16x32_bf16 v[6:9], v[194:197], v[186:189], v[6:9]
	v_mfma_f32_16x16x32_bf16 v[2:5], v[226:229], v[186:189], v[2:5]
	s_barrier
	s_cbranch_scc0 .LBB0_182
